# grid barrier: non-last arrivers of an XCD issue buffer_wbl2 while they wait (13 sites); on top of v038
# baseline (speedup 1.0000x reference)
; __device__ __forceinline__ unsigned xb_ld(unsigned* p)              { return __hip_atomic_load(p, __ATOMIC_RELAXED, __HIP_MEMORY_SCOPE_AGENT); }
; __device__ __forceinline__ unsigned xb_add(unsigned* p, unsigned v) { return __hip_atomic_fetch_add(p, v, __ATOMIC_RELAXED, __HIP_MEMORY_SCOPE_AGENT); }
; #define XB_SPIN(cond, bar) do { unsigned _sp = 0; while (cond) { __builtin_amdgcn_s_sleep(1); \
;     if ((++_sp & 255u) == 0u) { if (xb_ld(&(bar)[XB_TMO])) break; if (_sp > XB_SPIN_CAP) { atomicAdd(&(bar)[XB_TMO], 1u); break; } } } } while (0)
; __device__ __forceinline__ void xcd_barrier(const XcdBarrier& b) {
;     ...
;         const unsigned old = xb_add(&bar[XB_XSUB(b.x)], 1u);
;         const unsigned gen = old / nloc;
;         if (old + 1u == (gen + 1u) * nloc) {
;             __builtin_amdgcn_fence(__ATOMIC_RELEASE, "agent");
;             asm volatile("s_waitcnt vmcnt(0)" ::: "memory");
;             const unsigned og = xb_add(&bar[XB_TOP], 1u);
;             const unsigned tg = og / nx;
;             if (og + 1u == (tg + 1u) * nx) xb_add(&bar[XB_TOPGEN], 1u);
;             else XB_SPIN(xb_ld(&bar[XB_TOPGEN]) == tg, bar);
;             __builtin_amdgcn_fence(__ATOMIC_ACQUIRE, "agent");
;             xb_add(&bar[XB_XGEN(b.x)], 1u);
;             asm volatile("s_waitcnt vmcnt(0)" ::: "memory");
;         } else {
;             XB_SPIN(xb_ld(&bar[XB_XGEN(b.x)]) == gen, bar);
;             __builtin_amdgcn_fence(__ATOMIC_ACQUIRE, "agent");
;             asm volatile("s_waitcnt vmcnt(0)" ::: "memory");
;         }
.LBB0_175:
	s_or_b64 exec, exec, s[12:13]
	s_waitcnt vmcnt(0)
	v_readfirstlane_b32 s2, v5
	v_sub_u32_e32 v6, 0, v4
	s_mov_b64 s[12:13], -1
	v_add_u32_e32 v5, s2, v2
	v_cvt_f32_u32_e32 v2, v4
	v_readlane_b32 s2, v255, 8
	v_readlane_b32 s3, v255, 9
	v_rcp_iflag_f32_e32 v2, v2
	s_nop 0
	v_mul_f32_e32 v2, 0x4f7ffffe, v2
	v_cvt_u32_f32_e32 v2, v2
	v_mul_lo_u32 v6, v6, v2
	v_mul_hi_u32 v6, v2, v6
	v_add_u32_e32 v2, v2, v6
	v_mul_hi_u32 v2, v5, v2
	v_mul_lo_u32 v6, v2, v4
	v_sub_u32_e32 v6, v5, v6
	v_cmp_ge_u32_e32 vcc, v6, v4
	v_add_u32_e32 v7, 1, v2
	v_add_u32_e32 v5, 1, v5
	v_cndmask_b32_e32 v2, v2, v7, vcc
	v_sub_u32_e32 v7, v6, v4
	v_cndmask_b32_e32 v6, v6, v7, vcc
	v_cmp_ge_u32_e32 vcc, v6, v4
	v_add_u32_e32 v6, 1, v2
	s_nop 0
	v_cndmask_b32_e32 v2, v2, v6, vcc
	v_mul_lo_u32 v6, v4, v2
	v_add_u32_e32 v4, v6, v4
	v_cmp_ne_u32_e32 vcc, v5, v4
	v_mov_b64_e32 v[4:5], s[2:3]
	s_and_saveexec_b64 s[2:3], vcc
	s_cbranch_execz .LBB0_187
	v_readlane_b32 s4, v255, 8
	v_readlane_b32 s5, v255, 9
	buffer_wbl2 sc1
	s_mov_b64 s[18:19], 0
	s_nop 3
	global_load_dword v4, v3, s[4:5] sc1
	s_waitcnt vmcnt(0)
	v_cmp_eq_u32_e32 vcc, v4, v2
	s_and_saveexec_b64 s[12:13], vcc
	s_cbranch_execz .LBB0_186
	s_mov_b32 s4, 1
	s_branch .LBB0_179

; __device__ __forceinline__ unsigned xb_ld(unsigned* p)              { return __hip_atomic_load(p, __ATOMIC_RELAXED, __HIP_MEMORY_SCOPE_AGENT); }
; __device__ __forceinline__ unsigned xb_add(unsigned* p, unsigned v) { return __hip_atomic_fetch_add(p, v, __ATOMIC_RELAXED, __HIP_MEMORY_SCOPE_AGENT); }
; #define XB_SPIN(cond, bar) do { unsigned _sp = 0; while (cond) { __builtin_amdgcn_s_sleep(1); \
;     if ((++_sp & 255u) == 0u) { if (xb_ld(&(bar)[XB_TMO])) break; if (_sp > XB_SPIN_CAP) { atomicAdd(&(bar)[XB_TMO], 1u); break; } } } } while (0)
; __device__ __forceinline__ void xcd_barrier(const XcdBarrier& b) {
;     ...
;         const unsigned old = xb_add(&bar[XB_XSUB(b.x)], 1u);
;         const unsigned gen = old / nloc;
;         if (old + 1u == (gen + 1u) * nloc) {
;             __builtin_amdgcn_fence(__ATOMIC_RELEASE, "agent");
;             asm volatile("s_waitcnt vmcnt(0)" ::: "memory");
;             const unsigned og = xb_add(&bar[XB_TOP], 1u);
;             const unsigned tg = og / nx;
;             if (og + 1u == (tg + 1u) * nx) xb_add(&bar[XB_TOPGEN], 1u);
;             else XB_SPIN(xb_ld(&bar[XB_TOPGEN]) == tg, bar);
;             __builtin_amdgcn_fence(__ATOMIC_ACQUIRE, "agent");
;             xb_add(&bar[XB_XGEN(b.x)], 1u);
;             asm volatile("s_waitcnt vmcnt(0)" ::: "memory");
;         } else {
;             XB_SPIN(xb_ld(&bar[XB_XGEN(b.x)]) == gen, bar);
;             __builtin_amdgcn_fence(__ATOMIC_ACQUIRE, "agent");
;             asm volatile("s_waitcnt vmcnt(0)" ::: "memory");
;         }
.LBB0_1849:
	s_or_b64 exec, exec, s[12:13]
	v_cvt_f32_u32_e32 v6, v4
	s_waitcnt vmcnt(0)
	v_readfirstlane_b32 s2, v5
	s_mov_b64 s[12:13], -1
	v_rcp_iflag_f32_e32 v6, v6
	v_add_u32_e32 v2, s2, v2
	v_add_u32_e32 v7, 1, v2
	v_readlane_b32 s2, v255, 8
	v_mul_f32_e32 v5, 0x4f7ffffe, v6
	v_cvt_u32_f32_e32 v5, v5
	v_sub_u32_e32 v6, 0, v4
	v_readlane_b32 s3, v255, 9
	v_mul_lo_u32 v6, v6, v5
	v_mul_hi_u32 v6, v5, v6
	v_add_u32_e32 v5, v5, v6
	v_mul_hi_u32 v5, v2, v5
	v_mul_lo_u32 v6, v5, v4
	v_sub_u32_e32 v2, v2, v6
	v_add_u32_e32 v8, 1, v5
	v_cmp_ge_u32_e32 vcc, v2, v4
	v_sub_u32_e32 v6, v2, v4
	s_nop 0
	v_cndmask_b32_e32 v5, v5, v8, vcc
	v_cndmask_b32_e32 v2, v2, v6, vcc
	v_add_u32_e32 v6, 1, v5
	v_cmp_ge_u32_e32 vcc, v2, v4
	s_nop 1
	v_cndmask_b32_e32 v2, v5, v6, vcc
	v_mul_lo_u32 v5, v4, v2
	v_add_u32_e32 v4, v5, v4
	v_cmp_ne_u32_e32 vcc, v7, v4
	v_mov_b64_e32 v[4:5], s[2:3]
	s_and_saveexec_b64 s[2:3], vcc
	s_cbranch_execz .LBB0_1861
	v_readlane_b32 s4, v255, 8
	v_readlane_b32 s5, v255, 9
	buffer_wbl2 sc1
	s_mov_b64 s[18:19], 0
	s_nop 3
	global_load_dword v4, v3, s[4:5] sc1
	s_waitcnt vmcnt(0)
	v_cmp_eq_u32_e32 vcc, v4, v2
	s_and_saveexec_b64 s[12:13], vcc
	s_cbranch_execz .LBB0_1860
	s_mov_b32 s4, 1
	s_branch .LBB0_1853
